# v53: v46 with the tightest flag polling (s_sleep 0) in the rwkv scan hand-off spin loops
# baseline (speedup 1.0000x reference)
.LBB0_3006:
	s_sleep 0
	s_cbranch_execz .LBB0_3011

.LBB0_3021:
	s_add_i32 s19, s19, 1
	s_cmp_gt_u32 s19, 0x400000
	s_cbranch_scc1 .LBB0_3018
	s_mov_b64 s[4:5], -1
	s_sleep 0
	s_branch .LBB0_3018
